# v54 + removed the s_setprio 1/0 toggles inside the GEMM K-loop (waves stay at default priority during the MFMA blocks)
# baseline (speedup 1.0000x reference)
; #define PG8_STAGE(bufoff, gbase, voff) do { _Pragma("unroll") for (int _i = 0; _i < 2; ++_i) \
;         __builtin_amdgcn_global_load_lds((const unsigned*)((const char*)(gbase) + (voff)[_i]), (PG8_LAS unsigned*)(lds + (bufoff) + ldsw + _i * 8192), 16, 0, 0); } while (0)
; #define PG8_LDA(dst, b, h) do { _Pragma("unroll") for (int m = 0; m < 4; ++m) _Pragma("unroll") for (int k = 0; k < 2; ++k) dst[m][k] = *(const PG8_LAS bf16x8*)(lds + PG8_SA(b, h) + aoff + m * 2048 + k * 1024); } while (0)
; #define PG8_LDB(dst, b, h) do { _Pragma("unroll") for (int n = 0; n < 2; ++n) _Pragma("unroll") for (int k = 0; k < 2; ++k) dst[n][k] = *(const PG8_LAS bf16x8*)(lds + PG8_SB(b, h) + boff + n * 2048 + k * 1024); } while (0)
; #define PG8_MMA(ai, bj, At, Bt) do { __builtin_amdgcn_s_setprio(1); _Pragma("unroll") for (int m = 0; m < 4; ++m) _Pragma("unroll") for (int n = 0; n < 2; ++n) _Pragma("unroll") for (int k = 0; k < 2; ++k) \
;         acc[ai][bj][m][n] = __builtin_amdgcn_mfma_f32_16x16x32_bf16(Bt[n][k], At[m][k], acc[ai][bj][m][n], 0, 0, 0); __builtin_amdgcn_s_setprio(0); } while (0)
; #define PG8_WAIT_V(n) asm volatile("s_waitcnt vmcnt(" #n ")" ::: "memory")
; #define PG8_BAR __builtin_amdgcn_s_barrier()
; template <class Epi, class Sched, bool ALIGN_EPI = false, bool SP2 = false>
; __device__ __forceinline__ void gemm_phase(PG8_LAS unsigned char* lds, const Gemm g, const Sched& S, const Epi& E, const int tid) {
;     ...
;         for (int t = 0; t < nt; t += 2) {
;             const bool last = (t == nt - 2);
;             const char* a1 = cA + (size_t)(t + 1) * kstep;
;             const char* a2 = last ? nA : cA + (size_t)(t + 2) * kstep; const char* b2 = last ? nB : cB + (size_t)(t + 2) * kstep;
;             const char* a3 = a2 + kstep; const char* b3 = b2 + kstep;
;             if (last && has_next) S.a_ready(nxt);
;             if constexpr (SP2) {
;             PG8_LDB(B0, 0, 0); PG8_LDB(B1, 0, 1); PG8_SCHED; PG8_LDA(At, 0, 0); PG8_STAGE(PG8_SA(1, 1), a1 + hstep, voffA);
;             PG8_WAIT_V(8); PG8_WAIT_L(0); PG8_BAR; PG8_MMA(0, 0, At, B0); PG8_MMA(0, 1, At, B1); PG8_BAR; PG8_SCHED;
;             PG8_LDA(At, 0, 1); PG8_STAGE(PG8_SB(0, 0), b2, voffB); PG8_STAGE(PG8_SB(0, 1), b2 + hstep, voffB); PG8_STAGE(PG8_SA(0, 0), a2, voffA);
;             PG8_WAIT_V(8); PG8_WAIT_L(0); PG8_BAR; PG8_MMA(1, 0, At, B0); PG8_MMA(1, 1, At, B1); PG8_BAR; PG8_SCHED;
.LBB0_544:
	s_add_i32 s30, s2, 2
	s_add_u32 s31, s0, 0x80
	s_addc_u32 s3, s1, 0
	s_add_i32 s42, 0, 0x10000
	s_cmp_eq_u32 s27, s2
	s_cselect_b32 s3, s91, s3
	s_cselect_b32 s2, s90, s31
	v_add_u32_e32 v0, s42, v13
	s_cselect_b32 s41, s53, s29
	s_cselect_b32 s40, s52, s28
	s_add_i32 s31, 0, 0x14000
	ds_read_b128 v[142:145], v0
	ds_read_b128 v[146:149], v0 offset:1024
	ds_read_b128 v[150:153], v0 offset:2048
	ds_read_b128 v[154:157], v0 offset:3072
	v_add_u32_e32 v0, s31, v13
	ds_read_b128 v[158:161], v0
	ds_read_b128 v[162:165], v0 offset:1024
	ds_read_b128 v[166:169], v0 offset:2048
	ds_read_b128 v[170:173], v0 offset:3072
	v_lshl_add_u64 v[192:193], s[0:1], 0, v[184:185]
	s_add_i32 m0, s9, 0xc000
	ds_read_b128 v[174:177], v197
	ds_read_b128 v[178:181], v197 offset:1024
	ds_read_b128 v[188:191], v197 offset:2048
	ds_read_b128 v[198:201], v197 offset:3072
	ds_read_b128 v[202:205], v197 offset:4096
	ds_read_b128 v[206:209], v197 offset:5120
	ds_read_b128 v[222:225], v197 offset:6144
	ds_read_b128 v[226:229], v197 offset:7168
	global_load_lds_dwordx4 v[192:193], off
	v_lshl_add_u64 v[192:193], s[0:1], 0, v[186:187]
	s_add_i32 m0, s9, 0xe000
	s_nop 0
	global_load_lds_dwordx4 v[192:193], off
	s_waitcnt vmcnt(8)
	s_waitcnt lgkmcnt(0)
	s_barrier
	s_waitcnt lgkmcnt(0)
	v_mfma_f32_16x16x32_bf16 v[138:141], v[142:145], v[174:177], v[138:141]
	v_mfma_f32_16x16x32_bf16 v[134:137], v[150:153], v[174:177], v[134:137]
	v_mfma_f32_16x16x32_bf16 v[130:133], v[142:145], v[188:191], v[130:133]
	v_mfma_f32_16x16x32_bf16 v[126:129], v[150:153], v[188:191], v[126:129]
	v_mfma_f32_16x16x32_bf16 v[118:121], v[142:145], v[202:205], v[118:121]
	v_mfma_f32_16x16x32_bf16 v[110:113], v[150:153], v[202:205], v[110:113]
	v_mfma_f32_16x16x32_bf16 v[102:105], v[142:145], v[222:225], v[102:105]
	v_mfma_f32_16x16x32_bf16 v[94:97], v[150:153], v[222:225], v[94:97]
	v_mfma_f32_16x16x32_bf16 v[138:141], v[146:149], v[178:181], v[138:141]
	v_mfma_f32_16x16x32_bf16 v[134:137], v[154:157], v[178:181], v[134:137]
	v_mfma_f32_16x16x32_bf16 v[130:133], v[146:149], v[198:201], v[130:133]
	v_mfma_f32_16x16x32_bf16 v[126:129], v[154:157], v[198:201], v[126:129]
	v_mfma_f32_16x16x32_bf16 v[118:121], v[146:149], v[206:209], v[118:121]
	v_mfma_f32_16x16x32_bf16 v[110:113], v[154:157], v[206:209], v[110:113]
	v_mfma_f32_16x16x32_bf16 v[102:105], v[146:149], v[226:229], v[102:105]
	v_mfma_f32_16x16x32_bf16 v[94:97], v[154:157], v[226:229], v[94:97]
	v_mfma_f32_16x16x32_bf16 v[122:125], v[158:161], v[174:177], v[122:125]
	v_mfma_f32_16x16x32_bf16 v[114:117], v[166:169], v[174:177], v[114:117]
	v_mfma_f32_16x16x32_bf16 v[106:109], v[158:161], v[188:191], v[106:109]
	v_mfma_f32_16x16x32_bf16 v[98:101], v[166:169], v[188:191], v[98:101]
	v_mfma_f32_16x16x32_bf16 v[90:93], v[158:161], v[202:205], v[90:93]
	v_mfma_f32_16x16x32_bf16 v[86:89], v[166:169], v[202:205], v[86:89]
	v_mfma_f32_16x16x32_bf16 v[82:85], v[158:161], v[222:225], v[82:85]
	v_mfma_f32_16x16x32_bf16 v[78:81], v[166:169], v[222:225], v[78:81]
	v_mfma_f32_16x16x32_bf16 v[122:125], v[162:165], v[178:181], v[122:125]
	v_mfma_f32_16x16x32_bf16 v[114:117], v[170:173], v[178:181], v[114:117]
	v_mfma_f32_16x16x32_bf16 v[106:109], v[162:165], v[198:201], v[106:109]
	v_mfma_f32_16x16x32_bf16 v[98:101], v[170:173], v[198:201], v[98:101]
	v_mfma_f32_16x16x32_bf16 v[90:93], v[162:165], v[206:209], v[90:93]
	v_mfma_f32_16x16x32_bf16 v[86:89], v[170:173], v[206:209], v[86:89]
	v_mfma_f32_16x16x32_bf16 v[82:85], v[162:165], v[226:229], v[82:85]
	v_mfma_f32_16x16x32_bf16 v[78:81], v[170:173], v[226:229], v[78:81]
	s_barrier
	s_add_i32 s42, s42, s8
	v_lshl_add_u64 v[192:193], s[40:41], 0, v[6:7]
	s_mov_b32 m0, s42
	ds_read_b128 v[174:177], v197 offset:16384
	ds_read_b128 v[178:181], v197 offset:17408
	ds_read_b128 v[188:191], v197 offset:18432
	ds_read_b128 v[198:201], v197 offset:19456
	ds_read_b128 v[202:205], v197 offset:20480
	ds_read_b128 v[206:209], v197 offset:21504
	ds_read_b128 v[222:225], v197 offset:22528
	ds_read_b128 v[226:229], v197 offset:23552
	global_load_lds_dwordx4 v[192:193], off
	s_add_i32 m0, s42, 0x2000
	v_lshl_add_u64 v[210:211], s[40:41], 0, v[182:183]
	s_add_u32 s40, s40, s62
	s_addc_u32 s41, s41, 0
	s_add_i32 s31, s31, s8
	global_load_lds_dwordx4 v[210:211], off
	v_lshl_add_u64 v[230:231], s[40:41], 0, v[6:7]
	s_mov_b32 m0, s31
	v_lshl_add_u64 v[232:233], s[40:41], 0, v[182:183]
	global_load_lds_dwordx4 v[230:231], off
	s_add_i32 m0, s31, 0x2000
	v_lshl_add_u64 v[234:235], s[2:3], 0, v[2:3]
	global_load_lds_dwordx4 v[232:233], off
	s_mov_b32 m0, s9
	v_lshl_add_u64 v[236:237], s[2:3], 0, v[10:11]
	global_load_lds_dwordx4 v[234:235], off
	s_mov_b32 m0, s14
	s_nop 0
	global_load_lds_dwordx4 v[236:237], off
	s_waitcnt vmcnt(8)
	s_waitcnt lgkmcnt(0)
	s_barrier
; #define PG8_STAGE(bufoff, gbase, voff) do { _Pragma("unroll") for (int _i = 0; _i < 2; ++_i) \
;         __builtin_amdgcn_global_load_lds((const unsigned*)((const char*)(gbase) + (voff)[_i]), (PG8_LAS unsigned*)(lds + (bufoff) + ldsw + _i * 8192), 16, 0, 0); } while (0)
; #define PG8_LDA(dst, b, h) do { _Pragma("unroll") for (int m = 0; m < 4; ++m) _Pragma("unroll") for (int k = 0; k < 2; ++k) dst[m][k] = *(const PG8_LAS bf16x8*)(lds + PG8_SA(b, h) + aoff + m * 2048 + k * 1024); } while (0)
; #define PG8_LDB(dst, b, h) do { _Pragma("unroll") for (int n = 0; n < 2; ++n) _Pragma("unroll") for (int k = 0; k < 2; ++k) dst[n][k] = *(const PG8_LAS bf16x8*)(lds + PG8_SB(b, h) + boff + n * 2048 + k * 1024); } while (0)
; #define PG8_MMA(ai, bj, At, Bt) do { __builtin_amdgcn_s_setprio(1); _Pragma("unroll") for (int m = 0; m < 4; ++m) _Pragma("unroll") for (int n = 0; n < 2; ++n) _Pragma("unroll") for (int k = 0; k < 2; ++k) \
;         acc[ai][bj][m][n] = __builtin_amdgcn_mfma_f32_16x16x32_bf16(Bt[n][k], At[m][k], acc[ai][bj][m][n], 0, 0, 0); __builtin_amdgcn_s_setprio(0); } while (0)
; #define PG8_WAIT_V(n) asm volatile("s_waitcnt vmcnt(" #n ")" ::: "memory")
; #define PG8_WAIT_L(n) asm volatile("s_waitcnt lgkmcnt(" #n ")" ::: "memory")
; #define PG8_BAR __builtin_amdgcn_s_barrier()
; #define PG8_SCHED __builtin_amdgcn_sched_barrier(0)
; template <class Epi, class Sched, bool ALIGN_EPI = false, bool SP2 = false>
; __device__ __forceinline__ void gemm_phase(PG8_LAS unsigned char* lds, const Gemm g, const Sched& S, const Epi& E, const int tid) {
;     ...
;             PG8_WAIT_V(8); PG8_WAIT_L(0); PG8_BAR; PG8_MMA(1, 0, At, B0); PG8_MMA(1, 1, At, B1); PG8_BAR; PG8_SCHED;
;             PG8_LDB(B0, 1, 0); PG8_LDB(B1, 1, 1); PG8_SCHED; PG8_LDA(At, 1, 0); PG8_STAGE(PG8_SA(0, 1), a2 + hstep, voffA);
;             PG8_WAIT_V(8); PG8_WAIT_L(0); PG8_BAR; PG8_MMA(0, 0, At, B0); PG8_MMA(0, 1, At, B1); PG8_BAR; PG8_SCHED;
	s_waitcnt lgkmcnt(0)
	v_mfma_f32_16x16x32_bf16 v[74:77], v[142:145], v[174:177], v[74:77]
	v_mfma_f32_16x16x32_bf16 v[70:73], v[150:153], v[174:177], v[70:73]
	v_mfma_f32_16x16x32_bf16 v[66:69], v[142:145], v[188:191], v[66:69]
	v_mfma_f32_16x16x32_bf16 v[62:65], v[150:153], v[188:191], v[62:65]
	v_mfma_f32_16x16x32_bf16 v[50:53], v[142:145], v[202:205], v[50:53]
	v_mfma_f32_16x16x32_bf16 v[46:49], v[150:153], v[202:205], v[46:49]
	v_mfma_f32_16x16x32_bf16 v[34:37], v[142:145], v[222:225], v[34:37]
	v_mfma_f32_16x16x32_bf16 v[30:33], v[150:153], v[222:225], v[30:33]
	v_mfma_f32_16x16x32_bf16 v[74:77], v[146:149], v[178:181], v[74:77]
	v_mfma_f32_16x16x32_bf16 v[70:73], v[154:157], v[178:181], v[70:73]
	v_mfma_f32_16x16x32_bf16 v[66:69], v[146:149], v[198:201], v[66:69]
	v_mfma_f32_16x16x32_bf16 v[62:65], v[154:157], v[198:201], v[62:65]
	v_mfma_f32_16x16x32_bf16 v[50:53], v[146:149], v[206:209], v[50:53]
	v_mfma_f32_16x16x32_bf16 v[46:49], v[154:157], v[206:209], v[46:49]
	v_mfma_f32_16x16x32_bf16 v[34:37], v[146:149], v[226:229], v[34:37]
	v_mfma_f32_16x16x32_bf16 v[30:33], v[154:157], v[226:229], v[30:33]
	v_mfma_f32_16x16x32_bf16 v[58:61], v[158:161], v[174:177], v[58:61]
	v_mfma_f32_16x16x32_bf16 v[54:57], v[166:169], v[174:177], v[54:57]
	v_mfma_f32_16x16x32_bf16 v[42:45], v[158:161], v[188:191], v[42:45]
	v_mfma_f32_16x16x32_bf16 v[38:41], v[166:169], v[188:191], v[38:41]
	v_mfma_f32_16x16x32_bf16 v[26:29], v[158:161], v[202:205], v[26:29]
	v_mfma_f32_16x16x32_bf16 v[22:25], v[166:169], v[202:205], v[22:25]
	v_mfma_f32_16x16x32_bf16 v[18:21], v[158:161], v[222:225], v[18:21]
	v_mfma_f32_16x16x32_bf16 v[14:17], v[166:169], v[222:225], v[14:17]
	v_mfma_f32_16x16x32_bf16 v[58:61], v[162:165], v[178:181], v[58:61]
	v_mfma_f32_16x16x32_bf16 v[54:57], v[170:173], v[178:181], v[54:57]
	v_mfma_f32_16x16x32_bf16 v[42:45], v[162:165], v[198:201], v[42:45]
	v_mfma_f32_16x16x32_bf16 v[38:41], v[170:173], v[198:201], v[38:41]
	v_mfma_f32_16x16x32_bf16 v[26:29], v[162:165], v[206:209], v[26:29]
	v_mfma_f32_16x16x32_bf16 v[22:25], v[170:173], v[206:209], v[22:25]
	v_mfma_f32_16x16x32_bf16 v[18:21], v[162:165], v[226:229], v[18:21]
	v_mfma_f32_16x16x32_bf16 v[14:17], v[170:173], v[226:229], v[14:17]
	s_barrier
	s_add_i32 s31, 0, 0x18000
	v_add_u32_e32 v0, s31, v13
	s_add_i32 s40, 0, 0x1c000
	ds_read_b128 v[142:145], v0
	ds_read_b128 v[146:149], v0 offset:1024
	ds_read_b128 v[150:153], v0 offset:2048
	ds_read_b128 v[154:157], v0 offset:3072
	v_add_u32_e32 v0, s40, v13
	ds_read_b128 v[158:161], v0
	ds_read_b128 v[162:165], v0 offset:1024
	ds_read_b128 v[166:169], v0 offset:2048
	ds_read_b128 v[170:173], v0 offset:3072
	s_add_u32 s2, s2, s62
	s_addc_u32 s3, s3, 0
	s_mov_b32 m0, s13
	v_lshl_add_u64 v[238:239], s[2:3], 0, v[2:3]
	ds_read_b128 v[174:177], v197 offset:32768
	ds_read_b128 v[178:181], v197 offset:33792
	ds_read_b128 v[188:191], v197 offset:34816
	ds_read_b128 v[198:201], v197 offset:35840
	ds_read_b128 v[202:205], v197 offset:36864
	ds_read_b128 v[206:209], v197 offset:37888
	ds_read_b128 v[222:225], v197 offset:38912
	ds_read_b128 v[226:229], v197 offset:39936
	global_load_lds_dwordx4 v[238:239], off
	v_lshl_add_u64 v[238:239], s[2:3], 0, v[10:11]
	s_mov_b32 m0, s58
	s_nop 0
	global_load_lds_dwordx4 v[238:239], off
	s_waitcnt vmcnt(8)
	s_waitcnt lgkmcnt(0)
	s_barrier
	s_waitcnt lgkmcnt(0)
	v_mfma_f32_16x16x32_bf16 v[138:141], v[142:145], v[174:177], v[138:141]
	v_mfma_f32_16x16x32_bf16 v[134:137], v[150:153], v[174:177], v[134:137]
	v_mfma_f32_16x16x32_bf16 v[130:133], v[142:145], v[188:191], v[130:133]
	v_mfma_f32_16x16x32_bf16 v[126:129], v[150:153], v[188:191], v[126:129]
	v_mfma_f32_16x16x32_bf16 v[118:121], v[142:145], v[202:205], v[118:121]
	v_mfma_f32_16x16x32_bf16 v[110:113], v[150:153], v[202:205], v[110:113]
	v_mfma_f32_16x16x32_bf16 v[102:105], v[142:145], v[222:225], v[102:105]
	v_mfma_f32_16x16x32_bf16 v[94:97], v[150:153], v[222:225], v[94:97]
	v_mfma_f32_16x16x32_bf16 v[138:141], v[146:149], v[178:181], v[138:141]
	v_mfma_f32_16x16x32_bf16 v[134:137], v[154:157], v[178:181], v[134:137]
	v_mfma_f32_16x16x32_bf16 v[130:133], v[146:149], v[198:201], v[130:133]
	v_mfma_f32_16x16x32_bf16 v[126:129], v[154:157], v[198:201], v[126:129]
	v_mfma_f32_16x16x32_bf16 v[118:121], v[146:149], v[206:209], v[118:121]
	v_mfma_f32_16x16x32_bf16 v[110:113], v[154:157], v[206:209], v[110:113]
	v_mfma_f32_16x16x32_bf16 v[102:105], v[146:149], v[226:229], v[102:105]
	v_mfma_f32_16x16x32_bf16 v[94:97], v[154:157], v[226:229], v[94:97]
	v_mfma_f32_16x16x32_bf16 v[122:125], v[158:161], v[174:177], v[122:125]
	v_mfma_f32_16x16x32_bf16 v[114:117], v[166:169], v[174:177], v[114:117]
	v_mfma_f32_16x16x32_bf16 v[106:109], v[158:161], v[188:191], v[106:109]
	v_mfma_f32_16x16x32_bf16 v[98:101], v[166:169], v[188:191], v[98:101]
	v_mfma_f32_16x16x32_bf16 v[90:93], v[158:161], v[202:205], v[90:93]
	v_mfma_f32_16x16x32_bf16 v[86:89], v[166:169], v[202:205], v[86:89]
	v_mfma_f32_16x16x32_bf16 v[82:85], v[158:161], v[222:225], v[82:85]
	v_mfma_f32_16x16x32_bf16 v[78:81], v[166:169], v[222:225], v[78:81]
	v_mfma_f32_16x16x32_bf16 v[122:125], v[162:165], v[178:181], v[122:125]
	v_mfma_f32_16x16x32_bf16 v[114:117], v[170:173], v[178:181], v[114:117]
	v_mfma_f32_16x16x32_bf16 v[106:109], v[162:165], v[198:201], v[106:109]
	v_mfma_f32_16x16x32_bf16 v[98:101], v[170:173], v[198:201], v[98:101]
	v_mfma_f32_16x16x32_bf16 v[90:93], v[162:165], v[206:209], v[90:93]
	v_mfma_f32_16x16x32_bf16 v[86:89], v[170:173], v[206:209], v[86:89]
	v_mfma_f32_16x16x32_bf16 v[82:85], v[162:165], v[226:229], v[82:85]
	v_mfma_f32_16x16x32_bf16 v[78:81], v[170:173], v[226:229], v[78:81]
	s_barrier
; #define PG8_STAGE(bufoff, gbase, voff) do { _Pragma("unroll") for (int _i = 0; _i < 2; ++_i) \
;         __builtin_amdgcn_global_load_lds((const unsigned*)((const char*)(gbase) + (voff)[_i]), (PG8_LAS unsigned*)(lds + (bufoff) + ldsw + _i * 8192), 16, 0, 0); } while (0)
; #define PG8_LDA(dst, b, h) do { _Pragma("unroll") for (int m = 0; m < 4; ++m) _Pragma("unroll") for (int k = 0; k < 2; ++k) dst[m][k] = *(const PG8_LAS bf16x8*)(lds + PG8_SA(b, h) + aoff + m * 2048 + k * 1024); } while (0)
; #define PG8_MMA(ai, bj, At, Bt) do { __builtin_amdgcn_s_setprio(1); _Pragma("unroll") for (int m = 0; m < 4; ++m) _Pragma("unroll") for (int n = 0; n < 2; ++n) _Pragma("unroll") for (int k = 0; k < 2; ++k) \
;         acc[ai][bj][m][n] = __builtin_amdgcn_mfma_f32_16x16x32_bf16(Bt[n][k], At[m][k], acc[ai][bj][m][n], 0, 0, 0); __builtin_amdgcn_s_setprio(0); } while (0)
; #define PG8_WAIT_V(n) asm volatile("s_waitcnt vmcnt(" #n ")" ::: "memory")
; #define PG8_WAIT_L(n) asm volatile("s_waitcnt lgkmcnt(" #n ")" ::: "memory")
; #define PG8_BAR __builtin_amdgcn_s_barrier()
; #define PG8_SCHED __builtin_amdgcn_sched_barrier(0)
; template <class Epi, class Sched, bool ALIGN_EPI = false, bool SP2 = false>
; __device__ __forceinline__ void gemm_phase(PG8_LAS unsigned char* lds, const Gemm g, const Sched& S, const Epi& E, const int tid) {
;     ...
;             PG8_LDA(At, 1, 1); PG8_STAGE(PG8_SB(1, 0), b3, voffB); PG8_STAGE(PG8_SB(1, 1), b3 + hstep, voffB); PG8_STAGE(PG8_SA(1, 0), a3, voffA);
;             PG8_WAIT_V(8); PG8_WAIT_L(0); PG8_BAR; PG8_MMA(1, 0, At, B0); PG8_MMA(1, 1, At, B1); PG8_BAR; PG8_SCHED;
;     ...
;         }
;         if constexpr (ALIGN_EPI) { if (wr == 0) PG8_BAR; }
	s_add_i32 s2, s31, s8
	v_lshl_add_u64 v[192:193], v[192:193], 0, s[96:97]
	s_mov_b32 m0, s2
	ds_read_b128 v[174:177], v197 offset:49152
	ds_read_b128 v[178:181], v197 offset:50176
	ds_read_b128 v[188:191], v197 offset:51200
	ds_read_b128 v[198:201], v197 offset:52224
	ds_read_b128 v[202:205], v197 offset:53248
	ds_read_b128 v[206:209], v197 offset:54272
	ds_read_b128 v[222:225], v197 offset:55296
	ds_read_b128 v[226:229], v197 offset:56320
	global_load_lds_dwordx4 v[192:193], off
	v_lshl_add_u64 v[192:193], v[210:211], 0, s[96:97]
	s_add_i32 m0, s2, 0x2000
	s_add_i32 s2, s40, s8
	global_load_lds_dwordx4 v[192:193], off
	v_lshl_add_u64 v[192:193], v[230:231], 0, s[96:97]
	s_mov_b32 m0, s2
	s_nop 0
	global_load_lds_dwordx4 v[192:193], off
	v_lshl_add_u64 v[192:193], v[232:233], 0, s[96:97]
	s_add_i32 m0, s2, 0x2000
	s_nop 0
	global_load_lds_dwordx4 v[192:193], off
	v_lshl_add_u64 v[192:193], v[234:235], 0, s[96:97]
	s_mov_b32 m0, s85
	s_nop 0
	global_load_lds_dwordx4 v[192:193], off
	v_lshl_add_u64 v[192:193], v[236:237], 0, s[96:97]
	s_mov_b32 m0, s59
	s_nop 0
	global_load_lds_dwordx4 v[192:193], off
	s_waitcnt vmcnt(8)
	s_waitcnt lgkmcnt(0)
	s_barrier
	s_waitcnt lgkmcnt(0)
	v_mfma_f32_16x16x32_bf16 v[74:77], v[142:145], v[174:177], v[74:77]
	v_mfma_f32_16x16x32_bf16 v[70:73], v[150:153], v[174:177], v[70:73]
	v_mfma_f32_16x16x32_bf16 v[66:69], v[142:145], v[188:191], v[66:69]
	v_mfma_f32_16x16x32_bf16 v[62:65], v[150:153], v[188:191], v[62:65]
	v_mfma_f32_16x16x32_bf16 v[50:53], v[142:145], v[202:205], v[50:53]
	v_mfma_f32_16x16x32_bf16 v[46:49], v[150:153], v[202:205], v[46:49]
	v_mfma_f32_16x16x32_bf16 v[34:37], v[142:145], v[222:225], v[34:37]
	v_mfma_f32_16x16x32_bf16 v[30:33], v[150:153], v[222:225], v[30:33]
	v_mfma_f32_16x16x32_bf16 v[74:77], v[146:149], v[178:181], v[74:77]
	v_mfma_f32_16x16x32_bf16 v[70:73], v[154:157], v[178:181], v[70:73]
	v_mfma_f32_16x16x32_bf16 v[66:69], v[146:149], v[198:201], v[66:69]
	v_mfma_f32_16x16x32_bf16 v[62:65], v[154:157], v[198:201], v[62:65]
	v_mfma_f32_16x16x32_bf16 v[50:53], v[146:149], v[206:209], v[50:53]
	v_mfma_f32_16x16x32_bf16 v[46:49], v[154:157], v[206:209], v[46:49]
	v_mfma_f32_16x16x32_bf16 v[34:37], v[146:149], v[226:229], v[34:37]
	v_mfma_f32_16x16x32_bf16 v[30:33], v[154:157], v[226:229], v[30:33]
	v_mfma_f32_16x16x32_bf16 v[58:61], v[158:161], v[174:177], v[58:61]
	v_mfma_f32_16x16x32_bf16 v[54:57], v[166:169], v[174:177], v[54:57]
	v_mfma_f32_16x16x32_bf16 v[42:45], v[158:161], v[188:191], v[42:45]
	v_mfma_f32_16x16x32_bf16 v[38:41], v[166:169], v[188:191], v[38:41]
	v_mfma_f32_16x16x32_bf16 v[26:29], v[158:161], v[202:205], v[26:29]
	v_mfma_f32_16x16x32_bf16 v[22:25], v[166:169], v[202:205], v[22:25]
	v_mfma_f32_16x16x32_bf16 v[18:21], v[158:161], v[222:225], v[18:21]
	v_mfma_f32_16x16x32_bf16 v[14:17], v[166:169], v[222:225], v[14:17]
	v_mfma_f32_16x16x32_bf16 v[58:61], v[162:165], v[178:181], v[58:61]
	v_mfma_f32_16x16x32_bf16 v[54:57], v[170:173], v[178:181], v[54:57]
	v_mfma_f32_16x16x32_bf16 v[42:45], v[162:165], v[198:201], v[42:45]
	v_mfma_f32_16x16x32_bf16 v[38:41], v[170:173], v[198:201], v[38:41]
	v_mfma_f32_16x16x32_bf16 v[26:29], v[162:165], v[206:209], v[26:29]
	v_mfma_f32_16x16x32_bf16 v[22:25], v[170:173], v[206:209], v[22:25]
	v_mfma_f32_16x16x32_bf16 v[18:21], v[162:165], v[226:229], v[18:21]
	v_mfma_f32_16x16x32_bf16 v[14:17], v[170:173], v[226:229], v[14:17]
	s_barrier
	s_add_u32 s0, s0, 0x100
	s_addc_u32 s1, s1, 0
	s_add_u32 s28, s28, 0x100
	s_addc_u32 s29, s29, 0
	s_cmp_ge_i32 s30, s25
	s_mov_b32 s2, s30
	s_cbranch_scc0 .LBB0_544
	v_readlane_b32 s0, v250, 0
	v_readlane_b32 s1, v250, 1
	s_and_b64 vcc, exec, s[0:1]
	s_cbranch_vccz .LBB0_547
	s_barrier
